# A/B: every per-cluster s_setprio 1/0 flip around MFMA groups deleted (no static raise)
# speedup vs baseline: 1.0020x; 1.0020x over previous
.Lres2_loop:
	s_waitcnt vmcnt(6)
	s_barrier
	s_add_i32 vcc_hi, s20, 2
	s_cmp_ge_u32 vcc_hi, 3
	s_cselect_b32 vcc_lo, 3, 0
	s_sub_i32 vcc_hi, vcc_hi, vcc_lo
	s_mul_i32 vcc_hi, vcc_hi, 0xc000
	s_add_i32 vcc_hi, vcc_hi, s26
	ds_read_b128 v[154:157], v86
	ds_read_b128 v[158:161], v86 offset:4096
	ds_read_b128 v[162:165], v128 offset:32768
	ds_read_b128 v[166:169], v128 offset:36864
	ds_read_b128 v[66:69], v87
	ds_read_b128 v[70:73], v87 offset:4096
	ds_read_b128 v[74:77], v129 offset:32768
	ds_read_b128 v[78:81], v129 offset:36864
	s_waitcnt lgkmcnt(4)
	v_mfma_f32_32x32x16_bf16 v[50:65], v[154:157], v[162:165], v[50:65]
	s_mov_b32 m0, vcc_hi
	v_mfma_f32_32x32x16_bf16 v[18:33], v[158:161], v[162:165], v[18:33]
	global_load_lds_dwordx4 v82, s[22:23]
	s_add_u32 m0, m0, 0x2000
	v_mfma_f32_32x32x16_bf16 v[34:49], v[154:157], v[166:169], v[34:49]
	global_load_lds_dwordx4 v83, s[22:23]
	s_add_u32 m0, m0, 0x2000
	v_mfma_f32_32x32x16_bf16 v[2:17], v[158:161], v[166:169], v[2:17]
	global_load_lds_dwordx4 v84, s[22:23]
	s_add_u32 m0, m0, 0x2000
	s_nop 0
	global_load_lds_dwordx4 v85, s[22:23]
	s_add_u32 m0, m0, 0x2000
	s_nop 0
	global_load_lds_dwordx4 v82, s[4:5]
	s_add_u32 m0, m0, 0x2000
	s_nop 0
	global_load_lds_dwordx4 v83, s[4:5]
	s_add_u32 s22, s22, 0x80
	s_addc_u32 s23, s23, 0
	s_add_u32 s4, s4, 0x80
	s_addc_u32 s5, s5, 0
	ds_read_b128 v[154:157], v88
	ds_read_b128 v[158:161], v88 offset:4096
	ds_read_b128 v[162:165], v130 offset:32768
	ds_read_b128 v[166:169], v130 offset:36864
	s_waitcnt lgkmcnt(4)
	v_mfma_f32_32x32x16_bf16 v[50:65], v[66:69], v[74:77], v[50:65]
	v_mfma_f32_32x32x16_bf16 v[18:33], v[70:73], v[74:77], v[18:33]
	v_mfma_f32_32x32x16_bf16 v[34:49], v[66:69], v[78:81], v[34:49]
	v_mfma_f32_32x32x16_bf16 v[2:17], v[70:73], v[78:81], v[2:17]
	ds_read_b128 v[66:69], v89
	ds_read_b128 v[70:73], v89 offset:4096
	ds_read_b128 v[74:77], v131 offset:32768
	ds_read_b128 v[78:81], v131 offset:36864
	s_waitcnt lgkmcnt(4)
	v_mfma_f32_32x32x16_bf16 v[50:65], v[154:157], v[162:165], v[50:65]
	v_mfma_f32_32x32x16_bf16 v[18:33], v[158:161], v[162:165], v[18:33]
	v_mfma_f32_32x32x16_bf16 v[34:49], v[154:157], v[166:169], v[34:49]
	v_mfma_f32_32x32x16_bf16 v[2:17], v[158:161], v[166:169], v[2:17]
	s_waitcnt lgkmcnt(0)
	v_mfma_f32_32x32x16_bf16 v[50:65], v[66:69], v[74:77], v[50:65]
	v_mfma_f32_32x32x16_bf16 v[18:33], v[70:73], v[74:77], v[18:33]
	v_mfma_f32_32x32x16_bf16 v[34:49], v[66:69], v[78:81], v[34:49]
	v_mfma_f32_32x32x16_bf16 v[2:17], v[70:73], v[78:81], v[2:17]
	s_add_i32 s20, s20, 1
	s_cmp_eq_u32 s20, 3
	s_cselect_b32 vcc_lo, 0xfffdc000, 0
	s_cselect_b32 s20, 0, s20
	s_add_i32 vcc_lo, vcc_lo, 0xc000
	v_add_u32_e32 v86, vcc_lo, v86
	v_add_u32_e32 v128, vcc_lo, v128
	v_add_u32_e32 v87, vcc_lo, v87
	v_add_u32_e32 v129, vcc_lo, v129
	v_add_u32_e32 v88, vcc_lo, v88
	v_add_u32_e32 v130, vcc_lo, v130
	v_add_u32_e32 v89, vcc_lo, v89
	v_add_u32_e32 v131, vcc_lo, v131
	s_add_i32 s25, s25, -1
	s_cmp_lg_u32 s25, 0
	s_cbranch_scc1 .Lres2_loop
	s_waitcnt vmcnt(6)
	s_barrier
	ds_read_b128 v[154:157], v86
	ds_read_b128 v[158:161], v86 offset:4096
	ds_read_b128 v[162:165], v128 offset:32768
	ds_read_b128 v[166:169], v128 offset:36864
	ds_read_b128 v[66:69], v87
	ds_read_b128 v[70:73], v87 offset:4096
	ds_read_b128 v[74:77], v129 offset:32768
	ds_read_b128 v[78:81], v129 offset:36864
	s_waitcnt lgkmcnt(4)
	v_mfma_f32_32x32x16_bf16 v[50:65], v[154:157], v[162:165], v[50:65]
	v_mfma_f32_32x32x16_bf16 v[18:33], v[158:161], v[162:165], v[18:33]
	v_mfma_f32_32x32x16_bf16 v[34:49], v[154:157], v[166:169], v[34:49]
	v_mfma_f32_32x32x16_bf16 v[2:17], v[158:161], v[166:169], v[2:17]
	ds_read_b128 v[154:157], v88
	ds_read_b128 v[158:161], v88 offset:4096
	ds_read_b128 v[162:165], v130 offset:32768
	ds_read_b128 v[166:169], v130 offset:36864
	s_waitcnt lgkmcnt(4)
	v_mfma_f32_32x32x16_bf16 v[50:65], v[66:69], v[74:77], v[50:65]
	v_mfma_f32_32x32x16_bf16 v[18:33], v[70:73], v[74:77], v[18:33]
	v_mfma_f32_32x32x16_bf16 v[34:49], v[66:69], v[78:81], v[34:49]
	v_mfma_f32_32x32x16_bf16 v[2:17], v[70:73], v[78:81], v[2:17]
	ds_read_b128 v[66:69], v89
	ds_read_b128 v[70:73], v89 offset:4096
	ds_read_b128 v[74:77], v131 offset:32768
	ds_read_b128 v[78:81], v131 offset:36864
	s_waitcnt lgkmcnt(4)
	v_mfma_f32_32x32x16_bf16 v[50:65], v[154:157], v[162:165], v[50:65]
	v_mfma_f32_32x32x16_bf16 v[18:33], v[158:161], v[162:165], v[18:33]
	v_mfma_f32_32x32x16_bf16 v[34:49], v[154:157], v[166:169], v[34:49]
	v_mfma_f32_32x32x16_bf16 v[2:17], v[158:161], v[166:169], v[2:17]
	s_waitcnt lgkmcnt(0)
	v_mfma_f32_32x32x16_bf16 v[50:65], v[66:69], v[74:77], v[50:65]
	v_mfma_f32_32x32x16_bf16 v[18:33], v[70:73], v[74:77], v[18:33]
	v_mfma_f32_32x32x16_bf16 v[34:49], v[66:69], v[78:81], v[34:49]
	v_mfma_f32_32x32x16_bf16 v[2:17], v[70:73], v[78:81], v[2:17]
	s_add_i32 s20, s20, 1
	s_cmp_eq_u32 s20, 3
	s_cselect_b32 vcc_lo, 0xfffdc000, 0
	s_cselect_b32 s20, 0, s20
	s_add_i32 vcc_lo, vcc_lo, 0xc000
	v_add_u32_e32 v86, vcc_lo, v86
	v_add_u32_e32 v128, vcc_lo, v128
	v_add_u32_e32 v87, vcc_lo, v87
	v_add_u32_e32 v129, vcc_lo, v129
	v_add_u32_e32 v88, vcc_lo, v88
	v_add_u32_e32 v130, vcc_lo, v130
	v_add_u32_e32 v89, vcc_lo, v89
	v_add_u32_e32 v131, vcc_lo, v131
	s_waitcnt vmcnt(0)
	s_barrier
	ds_read_b128 v[154:157], v86
	ds_read_b128 v[158:161], v86 offset:4096
	ds_read_b128 v[162:165], v128 offset:32768
	ds_read_b128 v[166:169], v128 offset:36864
	ds_read_b128 v[66:69], v87
	ds_read_b128 v[70:73], v87 offset:4096
	ds_read_b128 v[74:77], v129 offset:32768
	ds_read_b128 v[78:81], v129 offset:36864
	s_waitcnt lgkmcnt(4)
	v_mfma_f32_32x32x16_bf16 v[50:65], v[154:157], v[162:165], v[50:65]
	v_mfma_f32_32x32x16_bf16 v[18:33], v[158:161], v[162:165], v[18:33]
	v_mfma_f32_32x32x16_bf16 v[34:49], v[154:157], v[166:169], v[34:49]
	v_mfma_f32_32x32x16_bf16 v[2:17], v[158:161], v[166:169], v[2:17]
	ds_read_b128 v[154:157], v88
	ds_read_b128 v[158:161], v88 offset:4096
	ds_read_b128 v[162:165], v130 offset:32768
	ds_read_b128 v[166:169], v130 offset:36864
	s_waitcnt lgkmcnt(4)
	v_mfma_f32_32x32x16_bf16 v[50:65], v[66:69], v[74:77], v[50:65]
	v_mfma_f32_32x32x16_bf16 v[18:33], v[70:73], v[74:77], v[18:33]
	v_mfma_f32_32x32x16_bf16 v[34:49], v[66:69], v[78:81], v[34:49]
	v_mfma_f32_32x32x16_bf16 v[2:17], v[70:73], v[78:81], v[2:17]
	ds_read_b128 v[66:69], v89
	ds_read_b128 v[70:73], v89 offset:4096
	ds_read_b128 v[74:77], v131 offset:32768
	ds_read_b128 v[78:81], v131 offset:36864
	s_waitcnt lgkmcnt(4)
	v_mfma_f32_32x32x16_bf16 v[50:65], v[154:157], v[162:165], v[50:65]
	v_mfma_f32_32x32x16_bf16 v[18:33], v[158:161], v[162:165], v[18:33]
	v_mfma_f32_32x32x16_bf16 v[34:49], v[154:157], v[166:169], v[34:49]
	v_mfma_f32_32x32x16_bf16 v[2:17], v[158:161], v[166:169], v[2:17]
	s_waitcnt lgkmcnt(0)
	v_mfma_f32_32x32x16_bf16 v[50:65], v[66:69], v[74:77], v[50:65]
	v_mfma_f32_32x32x16_bf16 v[18:33], v[70:73], v[74:77], v[18:33]
	v_mfma_f32_32x32x16_bf16 v[34:49], v[66:69], v[78:81], v[34:49]
	v_mfma_f32_32x32x16_bf16 v[2:17], v[70:73], v[78:81], v[2:17]
	s_barrier
	s_nop 7
	v_add_u32_e32 v68, s40, v142
	v_add_u32_e32 v66, 0xfffff000, v68
	v_lshrrev_b32_e32 v67, 11, v66
	s_movk_i32 s4, 0x1800
	s_movk_i32 s22, 0xfff
	v_mad_u32_u24 v153, v67, s4, s4
	v_cmp_lt_i32_e32 vcc, s22, v68
	v_ashrrev_i32_e32 v69, 31, v68
	v_readlane_b32 s4, v254, 0
	v_or_b32_e32 v66, s42, v143
	v_cndmask_b32_e32 v158, 0, v153, vcc
	v_lshlrev_b64 v[70:71], 12, v[68:69]
	v_readlane_b32 s5, v254, 1
	v_ashrrev_i32_e32 v67, 31, v66
	s_nop 0
	v_lshl_add_u64 v[72:73], s[4:5], 0, v[70:71]
	v_add_u32_e32 v70, v158, v66
	v_ashrrev_i32_e32 v71, 31, v70
	v_lshl_add_u64 v[70:71], v[70:71], 2, s[28:29]
	s_barrier
	global_load_dword v69, v[70:71], off
	v_lshlrev_b64 v[70:71], 2, v[66:67]
	v_lshl_add_u64 v[74:75], v[72:73], 0, v[70:71]
	v_mov_b32_e32 v111, v1
	v_lshl_add_u64 v[72:73], v[74:75], 0, v[0:1]
	v_mov_b32_e32 v99, v1
	v_mov_b32_e32 v101, v1
	v_mov_b32_e32 v103, v1
	v_mov_b32_e32 v105, v1
	v_mov_b32_e32 v107, v1
	v_mov_b32_e32 v109, v1
	v_lshl_add_u64 v[88:89], v[74:75], 0, v[110:111]
	v_mov_b32_e32 v113, v1
	v_lshl_add_u64 v[76:77], v[74:75], 0, v[98:99]
	v_lshl_add_u64 v[78:79], v[74:75], 0, v[100:101]
	v_lshl_add_u64 v[80:81], v[74:75], 0, v[102:103]
	v_lshl_add_u64 v[82:83], v[74:75], 0, v[104:105]
	v_lshl_add_u64 v[84:85], v[74:75], 0, v[106:107]
	v_lshl_add_u64 v[86:87], v[74:75], 0, v[108:109]
	global_load_dword v67, v[72:73], off
	global_load_dword v159, v[76:77], off
	global_load_dword v160, v[78:79], off
	global_load_dword v161, v[80:81], off
	global_load_dword v162, v[82:83], off
	global_load_dword v163, v[84:85], off
	global_load_dword v164, v[86:87], off
	global_load_dword v165, v[88:89], off
	v_lshl_add_u64 v[128:129], v[74:75], 0, v[112:113]
	v_mov_b32_e32 v115, v1
	global_load_dword v166, v[128:129], off
	v_lshl_add_u64 v[130:131], v[74:75], 0, v[114:115]
	v_mov_b32_e32 v117, v1
	global_load_dword v167, v[130:131], off
	v_lshl_add_u64 v[132:133], v[74:75], 0, v[116:117]
	v_mov_b32_e32 v119, v1
	global_load_dword v168, v[132:133], off
	v_lshl_add_u64 v[134:135], v[74:75], 0, v[118:119]
	v_mov_b32_e32 v121, v1
	global_load_dword v169, v[134:135], off
	v_lshl_add_u64 v[136:137], v[74:75], 0, v[120:121]
	v_mov_b32_e32 v123, v1
	global_load_dword v170, v[136:137], off
	v_lshl_add_u64 v[138:139], v[74:75], 0, v[122:123]
	v_mov_b32_e32 v125, v1
	global_load_dword v171, v[138:139], off
	global_load_dword v175, v[72:73], off offset:128
	v_lshl_add_u64 v[154:155], v[74:75], 0, v[124:125]
	v_mov_b32_e32 v127, v1
	global_load_dword v172, v[154:155], off
	v_lshl_add_u64 v[156:157], v[74:75], 0, v[126:127]
	global_load_dword v173, v[156:157], off
	v_add_f32_e32 v50, 0, v50
	v_readlane_b32 s8, v254, 4
	v_readlane_b32 s9, v254, 5
	v_add_f32_e32 v51, 0, v51
	v_add_f32_e32 v52, 0, v52
	v_add_f32_e32 v53, 0, v53
	v_add_f32_e32 v54, 0, v54
	v_add_f32_e32 v55, 0, v55
	v_add_f32_e32 v56, 0, v56
	v_or_b32_e32 v174, 32, v66
	s_mov_b64 s[8:9], 0x80
	v_add_f32_e32 v34, 0, v34
	v_add_f32_e32 v35, 0, v35
	v_add_f32_e32 v36, 0, v36
	v_add_f32_e32 v37, 0, v37
	v_add_f32_e32 v38, 0, v38
	v_add_f32_e32 v39, 0, v39
	v_add_f32_e32 v40, 0, v40
	v_add_f32_e32 v18, 0, v18
	v_add_f32_e32 v19, 0, v19
	v_add_f32_e32 v20, 0, v20
	v_add_f32_e32 v21, 0, v21
	v_add_f32_e32 v2, 0, v2
	s_add_i32 s1, s1, s0
	v_readlane_b32 s6, v254, 2
	v_readlane_b32 s7, v254, 3
	v_add_f32_e32 v3, 0, v3
	v_add_f32_e32 v4, 0, v4
	s_cmpk_gt_i32 s1, 0xff
	v_readlane_b32 s10, v254, 6
	v_readlane_b32 s11, v254, 7
	v_readlane_b32 s12, v254, 8
	v_readlane_b32 s13, v254, 9
	v_readlane_b32 s14, v254, 10
	v_readlane_b32 s15, v254, 11
	v_readlane_b32 s16, v254, 12
	v_readlane_b32 s17, v254, 13
	v_readlane_b32 s18, v254, 14
	v_readlane_b32 s19, v254, 15
	s_waitcnt vmcnt(16)
	v_fmac_f32_e32 v67, v50, v69
	v_add_f32_e32 v50, 0, v57
	s_waitcnt vmcnt(15)
	v_fmac_f32_e32 v159, v51, v69
	s_waitcnt vmcnt(14)
	v_fmac_f32_e32 v160, v52, v69
	s_waitcnt vmcnt(13)
	v_fmac_f32_e32 v161, v53, v69
	s_waitcnt vmcnt(12)
	v_fmac_f32_e32 v162, v54, v69
	s_waitcnt vmcnt(11)
	v_fmac_f32_e32 v163, v55, v69
	s_waitcnt vmcnt(9)
	v_fmac_f32_e32 v165, v50, v69
	v_add_f32_e32 v50, 0, v58
	v_fmac_f32_e32 v164, v56, v69
	s_waitcnt vmcnt(8)
	v_fmac_f32_e32 v166, v50, v69
	v_add_f32_e32 v50, 0, v59
	global_store_dword v[72:73], v67, off
	global_store_dword v[76:77], v159, off
	global_store_dword v[78:79], v160, off
	global_store_dword v[80:81], v161, off
	global_store_dword v[82:83], v162, off
	global_store_dword v[84:85], v163, off
	global_store_dword v[86:87], v164, off
	s_waitcnt vmcnt(14)
	v_fmac_f32_e32 v167, v50, v69
	v_add_f32_e32 v50, 0, v60
	v_add_f32_e32 v67, 0, v65
	s_waitcnt vmcnt(13)
	v_fmac_f32_e32 v168, v50, v69
	v_add_f32_e32 v50, 0, v61
	global_store_dword v[88:89], v165, off
	s_waitcnt vmcnt(13)
	v_fmac_f32_e32 v169, v50, v69
	v_add_f32_e32 v50, 0, v62
	global_store_dword v[128:129], v166, off
	s_waitcnt vmcnt(13)
	v_fmac_f32_e32 v170, v50, v69
	v_add_f32_e32 v50, 0, v63
	global_store_dword v[130:131], v167, off
	s_waitcnt vmcnt(13)
	v_fmac_f32_e32 v171, v50, v69
	v_add_f32_e32 v50, 0, v64
	global_store_dword v[132:133], v168, off
	global_store_dword v[134:135], v169, off
	s_waitcnt vmcnt(13)
	v_fmac_f32_e32 v172, v50, v69
	v_lshl_add_u64 v[50:51], v[74:75], 0, s[8:9]
	v_add_u32_e32 v74, v158, v174
	global_store_dword v[136:137], v170, off
	global_store_dword v[138:139], v171, off
	global_store_dword v[154:155], v172, off
	v_lshl_add_u64 v[52:53], v[50:51], 0, v[98:99]
	s_waitcnt vmcnt(15)
	v_fmac_f32_e32 v173, v67, v69
	v_ashrrev_i32_e32 v75, 31, v74
	v_lshl_add_u64 v[54:55], v[50:51], 0, v[100:101]
	v_lshl_add_u64 v[56:57], v[50:51], 0, v[102:103]
	v_lshl_add_u64 v[58:59], v[50:51], 0, v[104:105]
	v_lshl_add_u64 v[60:61], v[50:51], 0, v[106:107]
	v_lshl_add_u64 v[62:63], v[50:51], 0, v[108:109]
	v_lshl_add_u64 v[64:65], v[50:51], 0, v[110:111]
	global_load_dword v88, v[52:53], off
	global_load_dword v89, v[54:55], off
	global_load_dword v128, v[56:57], off
	global_load_dword v129, v[58:59], off
	global_load_dword v130, v[60:61], off
	global_load_dword v131, v[62:63], off
	global_load_dword v132, v[64:65], off
	v_lshl_add_u64 v[74:75], v[74:75], 2, s[28:29]
	global_store_dword v[156:157], v173, off
	global_load_dword v67, v[74:75], off
	v_lshl_add_u64 v[74:75], v[50:51], 0, v[112:113]
	global_load_dword v69, v[74:75], off
	v_lshl_add_u64 v[76:77], v[50:51], 0, v[114:115]
	global_load_dword v133, v[76:77], off
	v_lshl_add_u64 v[78:79], v[50:51], 0, v[116:117]
	global_load_dword v134, v[78:79], off
	v_lshl_add_u64 v[80:81], v[50:51], 0, v[118:119]
	global_load_dword v135, v[80:81], off
	v_lshl_add_u64 v[82:83], v[50:51], 0, v[120:121]
	global_load_dword v136, v[82:83], off
	v_lshl_add_u64 v[84:85], v[50:51], 0, v[122:123]
	global_load_dword v137, v[84:85], off
	v_lshl_add_u64 v[86:87], v[50:51], 0, v[124:125]
	global_load_dword v138, v[86:87], off
	v_lshl_add_u64 v[50:51], v[50:51], 0, v[126:127]
	global_load_dword v139, v[50:51], off
	s_waitcnt vmcnt(8)
	v_fmac_f32_e32 v175, v34, v67
	v_add_f32_e32 v34, 0, v41
	v_fmac_f32_e32 v132, v34, v67
	v_add_f32_e32 v34, 0, v42
	s_waitcnt vmcnt(7)
	v_fmac_f32_e32 v69, v34, v67
	v_add_f32_e32 v34, 0, v43
	s_waitcnt vmcnt(6)
	v_fmac_f32_e32 v133, v34, v67
	v_add_f32_e32 v34, 0, v44
	s_waitcnt vmcnt(5)
	v_fmac_f32_e32 v134, v34, v67
	v_add_f32_e32 v34, 0, v45
	s_waitcnt vmcnt(4)
	v_fmac_f32_e32 v135, v34, v67
	v_add_f32_e32 v34, 0, v46
	s_waitcnt vmcnt(3)
	v_fmac_f32_e32 v136, v34, v67
	v_add_f32_e32 v34, 0, v47
	s_waitcnt vmcnt(2)
	v_fmac_f32_e32 v137, v34, v67
	v_add_f32_e32 v34, 0, v48
	s_waitcnt vmcnt(1)
	v_fmac_f32_e32 v138, v34, v67
	v_add_f32_e32 v34, 0, v49
	s_waitcnt vmcnt(0)
	v_fmac_f32_e32 v139, v34, v67
	v_or_b32_e32 v34, 32, v68
	v_cmp_lt_i32_e32 vcc, s22, v34
	v_fmac_f32_e32 v88, v35, v67
	v_ashrrev_i32_e32 v35, 31, v34
	v_cndmask_b32_e32 v68, 0, v153, vcc
	v_fmac_f32_e32 v89, v36, v67
	v_lshlrev_b64 v[34:35], 12, v[34:35]
	v_add_u32_e32 v36, v68, v66
	v_fmac_f32_e32 v128, v37, v67
	v_lshl_add_u64 v[34:35], s[4:5], 0, v[34:35]
	v_ashrrev_i32_e32 v37, 31, v36
	v_fmac_f32_e32 v129, v38, v67
	v_fmac_f32_e32 v130, v39, v67
	v_fmac_f32_e32 v131, v40, v67
	global_store_dword v[72:73], v175, off offset:128
	global_store_dword v[52:53], v88, off
	global_store_dword v[54:55], v89, off
	global_store_dword v[56:57], v128, off
	global_store_dword v[58:59], v129, off
	global_store_dword v[60:61], v130, off
	global_store_dword v[62:63], v131, off
	global_store_dword v[64:65], v132, off
	global_store_dword v[74:75], v69, off
	global_store_dword v[76:77], v133, off
	global_store_dword v[78:79], v134, off
	global_store_dword v[80:81], v135, off
	global_store_dword v[82:83], v136, off
	global_store_dword v[84:85], v137, off
	global_store_dword v[86:87], v138, off
	global_store_dword v[50:51], v139, off
	v_lshl_add_u64 v[36:37], v[36:37], 2, s[28:29]
	v_lshl_add_u64 v[34:35], v[34:35], 0, v[70:71]
	global_load_dword v69, v[36:37], off
	v_lshl_add_u64 v[36:37], v[34:35], 0, v[0:1]
	v_lshl_add_u64 v[42:43], v[34:35], 0, v[102:103]
	v_lshl_add_u64 v[44:45], v[34:35], 0, v[104:105]
	v_lshl_add_u64 v[38:39], v[34:35], 0, v[98:99]
	v_lshl_add_u64 v[40:41], v[34:35], 0, v[100:101]
	global_load_dword v70, v[36:37], off
	global_load_dword v71, v[38:39], off
	global_load_dword v72, v[40:41], off
	global_load_dword v73, v[42:43], off
	global_load_dword v74, v[44:45], off
	v_lshl_add_u64 v[46:47], v[34:35], 0, v[106:107]
	global_load_dword v75, v[46:47], off
	v_lshl_add_u64 v[48:49], v[34:35], 0, v[108:109]
	global_load_dword v76, v[48:49], off
	v_lshl_add_u64 v[50:51], v[34:35], 0, v[110:111]
	global_load_dword v77, v[50:51], off
	v_lshl_add_u64 v[52:53], v[34:35], 0, v[112:113]
	global_load_dword v78, v[52:53], off
	v_lshl_add_u64 v[54:55], v[34:35], 0, v[114:115]
	global_load_dword v79, v[54:55], off
	global_load_dword v86, v[36:37], off offset:128
	v_lshl_add_u64 v[56:57], v[34:35], 0, v[116:117]
	global_load_dword v80, v[56:57], off
	v_lshl_add_u64 v[58:59], v[34:35], 0, v[118:119]
	global_load_dword v81, v[58:59], off
	v_lshl_add_u64 v[60:61], v[34:35], 0, v[120:121]
	global_load_dword v82, v[60:61], off
	v_lshl_add_u64 v[62:63], v[34:35], 0, v[122:123]
	global_load_dword v83, v[62:63], off
	v_lshl_add_u64 v[64:65], v[34:35], 0, v[124:125]
	global_load_dword v84, v[64:65], off
	v_lshl_add_u64 v[66:67], v[34:35], 0, v[126:127]
	global_load_dword v85, v[66:67], off
	s_waitcnt vmcnt(16)
	v_fmac_f32_e32 v70, v18, v69
	v_add_f32_e32 v18, 0, v22
	s_waitcnt vmcnt(15)
	v_fmac_f32_e32 v71, v19, v69
	s_waitcnt vmcnt(14)
	v_fmac_f32_e32 v72, v20, v69
	s_waitcnt vmcnt(12)
	v_fmac_f32_e32 v74, v18, v69
	v_add_f32_e32 v18, 0, v23
	s_waitcnt vmcnt(11)
	v_fmac_f32_e32 v75, v18, v69
	v_add_f32_e32 v18, 0, v24
	s_waitcnt vmcnt(10)
	v_fmac_f32_e32 v76, v18, v69
	v_add_f32_e32 v18, 0, v25
	s_waitcnt vmcnt(9)
	v_fmac_f32_e32 v77, v18, v69
	v_add_f32_e32 v18, 0, v26
	s_waitcnt vmcnt(8)
	v_fmac_f32_e32 v78, v18, v69
	v_add_f32_e32 v18, 0, v27
	s_waitcnt vmcnt(7)
	v_fmac_f32_e32 v79, v18, v69
	v_add_f32_e32 v18, 0, v28
	global_store_dword v[36:37], v70, off
	global_store_dword v[38:39], v71, off
	global_store_dword v[40:41], v72, off
	s_waitcnt vmcnt(8)
	v_fmac_f32_e32 v80, v18, v69
	v_add_f32_e32 v18, 0, v29
	s_waitcnt vmcnt(7)
	v_fmac_f32_e32 v81, v18, v69
	v_add_f32_e32 v18, 0, v30
	s_waitcnt vmcnt(6)
	v_fmac_f32_e32 v82, v18, v69
	v_add_f32_e32 v18, 0, v31
	s_waitcnt vmcnt(5)
	v_fmac_f32_e32 v83, v18, v69
	v_add_f32_e32 v18, 0, v32
	v_fmac_f32_e32 v73, v21, v69
	s_waitcnt vmcnt(4)
	v_fmac_f32_e32 v84, v18, v69
	v_add_f32_e32 v38, 0, v33
	v_lshl_add_u64 v[18:19], v[34:35], 0, s[8:9]
	v_add_u32_e32 v34, v68, v174
	global_store_dword v[42:43], v73, off
	global_store_dword v[44:45], v74, off
	global_store_dword v[46:47], v75, off
	global_store_dword v[48:49], v76, off
	global_store_dword v[50:51], v77, off
	global_store_dword v[52:53], v78, off
	global_store_dword v[54:55], v79, off
	global_store_dword v[56:57], v80, off
	global_store_dword v[58:59], v81, off
	global_store_dword v[60:61], v82, off
	global_store_dword v[62:63], v83, off
	global_store_dword v[64:65], v84, off
	v_lshl_add_u64 v[20:21], v[18:19], 0, v[98:99]
	s_waitcnt vmcnt(15)
	v_fmac_f32_e32 v85, v38, v69
	v_ashrrev_i32_e32 v35, 31, v34
	v_lshl_add_u64 v[22:23], v[18:19], 0, v[100:101]
	v_lshl_add_u64 v[24:25], v[18:19], 0, v[102:103]
	v_lshl_add_u64 v[26:27], v[18:19], 0, v[104:105]
	v_lshl_add_u64 v[28:29], v[18:19], 0, v[106:107]
	v_lshl_add_u64 v[30:31], v[18:19], 0, v[108:109]
	v_lshl_add_u64 v[32:33], v[18:19], 0, v[110:111]
	global_load_dword v50, v[20:21], off
	global_load_dword v51, v[22:23], off
	global_load_dword v52, v[24:25], off
	global_load_dword v53, v[26:27], off
	global_load_dword v54, v[28:29], off
	global_load_dword v55, v[30:31], off
	global_load_dword v56, v[32:33], off
	v_lshl_add_u64 v[34:35], v[34:35], 2, s[28:29]
	global_store_dword v[66:67], v85, off
	global_load_dword v57, v[34:35], off
	v_lshl_add_u64 v[34:35], v[18:19], 0, v[112:113]
	global_load_dword v58, v[34:35], off
	v_lshl_add_u64 v[38:39], v[18:19], 0, v[114:115]
	global_load_dword v59, v[38:39], off
	v_lshl_add_u64 v[40:41], v[18:19], 0, v[116:117]
	global_load_dword v60, v[40:41], off
	v_lshl_add_u64 v[42:43], v[18:19], 0, v[118:119]
	global_load_dword v61, v[42:43], off
	v_lshl_add_u64 v[44:45], v[18:19], 0, v[120:121]
	global_load_dword v62, v[44:45], off
	v_lshl_add_u64 v[46:47], v[18:19], 0, v[122:123]
	global_load_dword v63, v[46:47], off
	v_lshl_add_u64 v[48:49], v[18:19], 0, v[124:125]
	global_load_dword v64, v[48:49], off
	v_lshl_add_u64 v[18:19], v[18:19], 0, v[126:127]
	global_load_dword v65, v[18:19], off
	s_waitcnt vmcnt(8)
	v_fmac_f32_e32 v86, v2, v57
	v_add_f32_e32 v2, 0, v5
	v_fmac_f32_e32 v52, v2, v57
	v_add_f32_e32 v2, 0, v6
	v_fmac_f32_e32 v53, v2, v57
	v_add_f32_e32 v2, 0, v7
	v_fmac_f32_e32 v54, v2, v57
	v_add_f32_e32 v2, 0, v8
	v_fmac_f32_e32 v55, v2, v57
	v_add_f32_e32 v2, 0, v9
	v_fmac_f32_e32 v56, v2, v57
	v_add_f32_e32 v2, 0, v10
	s_waitcnt vmcnt(7)
	v_fmac_f32_e32 v58, v2, v57
	v_add_f32_e32 v2, 0, v11
	s_waitcnt vmcnt(6)
	v_fmac_f32_e32 v59, v2, v57
	v_add_f32_e32 v2, 0, v12
	s_waitcnt vmcnt(5)
	v_fmac_f32_e32 v60, v2, v57
	v_add_f32_e32 v2, 0, v13
	s_waitcnt vmcnt(4)
	v_fmac_f32_e32 v61, v2, v57
	v_add_f32_e32 v2, 0, v14
	s_waitcnt vmcnt(3)
	v_fmac_f32_e32 v62, v2, v57
	v_add_f32_e32 v2, 0, v15
	s_waitcnt vmcnt(2)
	v_fmac_f32_e32 v63, v2, v57
	v_add_f32_e32 v2, 0, v16
	s_waitcnt vmcnt(1)
	v_fmac_f32_e32 v64, v2, v57
	v_add_f32_e32 v2, 0, v17
	s_waitcnt vmcnt(0)
	v_fmac_f32_e32 v65, v2, v57
	v_fmac_f32_e32 v50, v3, v57
	v_fmac_f32_e32 v51, v4, v57
	global_store_dword v[36:37], v86, off offset:128
	global_store_dword v[20:21], v50, off
	global_store_dword v[22:23], v51, off
	global_store_dword v[24:25], v52, off
	global_store_dword v[26:27], v53, off
	global_store_dword v[28:29], v54, off
	global_store_dword v[30:31], v55, off
	global_store_dword v[32:33], v56, off
	global_store_dword v[34:35], v58, off
	global_store_dword v[38:39], v59, off
	global_store_dword v[40:41], v60, off
	global_store_dword v[42:43], v61, off
	global_store_dword v[44:45], v62, off
	global_store_dword v[46:47], v63, off
	global_store_dword v[48:49], v64, off
	global_store_dword v[18:19], v65, off
	s_cbranch_scc0 .LBB0_424

.Labin_loop:
	s_waitcnt vmcnt(6)
	s_barrier
	s_add_i32 vcc_hi, s26, 2
	s_cmp_ge_u32 vcc_hi, 3
	s_cselect_b32 vcc_lo, 3, 0
	s_sub_i32 vcc_hi, vcc_hi, vcc_lo
	s_mul_i32 vcc_hi, vcc_hi, 0xc000
	s_add_i32 vcc_hi, vcc_hi, s27
	ds_read_b128 v[4:7], v166
	ds_read_b128 v[8:11], v166 offset:4096
	ds_read_b128 v[12:15], v170 offset:32768
	ds_read_b128 v[142:145], v170 offset:36864
	ds_read_b128 v[146:149], v167
	ds_read_b128 v[150:153], v167 offset:4096
	ds_read_b128 v[154:157], v171 offset:32768
	ds_read_b128 v[158:161], v171 offset:36864
	s_waitcnt lgkmcnt(4)
	v_mfma_f32_32x32x16_bf16 v[32:47], v[4:7], v[12:15], v[32:47]
	s_mov_b32 m0, vcc_hi
	v_mfma_f32_32x32x16_bf16 v[16:31], v[8:11], v[12:15], v[16:31]
	global_load_lds_dwordx4 v162, s[22:23]
	s_add_u32 m0, m0, 0x2000
	v_mfma_f32_32x32x16_bf16 v[48:63], v[4:7], v[142:145], v[48:63]
	global_load_lds_dwordx4 v163, s[22:23]
	s_add_u32 m0, m0, 0x2000
	v_mfma_f32_32x32x16_bf16 v[64:79], v[8:11], v[142:145], v[64:79]
	global_load_lds_dwordx4 v164, s[22:23]
	s_add_u32 m0, m0, 0x2000
	s_nop 0
	global_load_lds_dwordx4 v165, s[22:23]
	s_add_u32 m0, m0, 0x2000
	s_nop 0
	global_load_lds_dwordx4 v162, s[24:25]
	s_add_u32 m0, m0, 0x2000
	s_nop 0
	global_load_lds_dwordx4 v163, s[24:25]
	s_add_u32 s22, s22, 0x80
	s_addc_u32 s23, s23, 0
	s_add_u32 s24, s24, 0x80
	s_addc_u32 s25, s25, 0
	ds_read_b128 v[4:7], v168
	ds_read_b128 v[8:11], v168 offset:4096
	ds_read_b128 v[12:15], v172 offset:32768
	ds_read_b128 v[142:145], v172 offset:36864
	s_waitcnt lgkmcnt(4)
	v_mfma_f32_32x32x16_bf16 v[32:47], v[146:149], v[154:157], v[32:47]
	v_mfma_f32_32x32x16_bf16 v[16:31], v[150:153], v[154:157], v[16:31]
	v_mfma_f32_32x32x16_bf16 v[48:63], v[146:149], v[158:161], v[48:63]
	v_mfma_f32_32x32x16_bf16 v[64:79], v[150:153], v[158:161], v[64:79]
	ds_read_b128 v[146:149], v169
	ds_read_b128 v[150:153], v169 offset:4096
	ds_read_b128 v[154:157], v173 offset:32768
	ds_read_b128 v[158:161], v173 offset:36864
	s_waitcnt lgkmcnt(4)
	v_mfma_f32_32x32x16_bf16 v[32:47], v[4:7], v[12:15], v[32:47]
	v_mfma_f32_32x32x16_bf16 v[16:31], v[8:11], v[12:15], v[16:31]
	v_mfma_f32_32x32x16_bf16 v[48:63], v[4:7], v[142:145], v[48:63]
	v_mfma_f32_32x32x16_bf16 v[64:79], v[8:11], v[142:145], v[64:79]
	s_waitcnt lgkmcnt(0)
	v_mfma_f32_32x32x16_bf16 v[32:47], v[146:149], v[154:157], v[32:47]
	v_mfma_f32_32x32x16_bf16 v[16:31], v[150:153], v[154:157], v[16:31]
	v_mfma_f32_32x32x16_bf16 v[48:63], v[146:149], v[158:161], v[48:63]
	v_mfma_f32_32x32x16_bf16 v[64:79], v[150:153], v[158:161], v[64:79]
	s_add_i32 s26, s26, 1
	s_cmp_eq_u32 s26, 3
	s_cselect_b32 vcc_lo, 0xfffdc000, 0
	s_cselect_b32 s26, 0, s26
	s_add_i32 vcc_lo, vcc_lo, 0xc000
	v_add_u32_e32 v166, vcc_lo, v166
	v_add_u32_e32 v170, vcc_lo, v170
	v_add_u32_e32 v167, vcc_lo, v167
	v_add_u32_e32 v171, vcc_lo, v171
	v_add_u32_e32 v168, vcc_lo, v168
	v_add_u32_e32 v172, vcc_lo, v172
	v_add_u32_e32 v169, vcc_lo, v169
	v_add_u32_e32 v173, vcc_lo, v173
	s_add_i32 s21, s21, -1
	s_cmp_lg_u32 s21, 0
	s_cbranch_scc1 .Labin_loop
	s_waitcnt vmcnt(6)
	s_barrier
	ds_read_b128 v[4:7], v166
	ds_read_b128 v[8:11], v166 offset:4096
	ds_read_b128 v[12:15], v170 offset:32768
	ds_read_b128 v[142:145], v170 offset:36864
	ds_read_b128 v[146:149], v167
	ds_read_b128 v[150:153], v167 offset:4096
	ds_read_b128 v[154:157], v171 offset:32768
	ds_read_b128 v[158:161], v171 offset:36864
	s_waitcnt lgkmcnt(4)
	v_mfma_f32_32x32x16_bf16 v[32:47], v[4:7], v[12:15], v[32:47]
	v_mfma_f32_32x32x16_bf16 v[16:31], v[8:11], v[12:15], v[16:31]
	v_mfma_f32_32x32x16_bf16 v[48:63], v[4:7], v[142:145], v[48:63]
	v_mfma_f32_32x32x16_bf16 v[64:79], v[8:11], v[142:145], v[64:79]
	ds_read_b128 v[4:7], v168
	ds_read_b128 v[8:11], v168 offset:4096
	ds_read_b128 v[12:15], v172 offset:32768
	ds_read_b128 v[142:145], v172 offset:36864
	s_waitcnt lgkmcnt(4)
	v_mfma_f32_32x32x16_bf16 v[32:47], v[146:149], v[154:157], v[32:47]
	v_mfma_f32_32x32x16_bf16 v[16:31], v[150:153], v[154:157], v[16:31]
	v_mfma_f32_32x32x16_bf16 v[48:63], v[146:149], v[158:161], v[48:63]
	v_mfma_f32_32x32x16_bf16 v[64:79], v[150:153], v[158:161], v[64:79]
	ds_read_b128 v[146:149], v169
	ds_read_b128 v[150:153], v169 offset:4096
	ds_read_b128 v[154:157], v173 offset:32768
	ds_read_b128 v[158:161], v173 offset:36864
	s_waitcnt lgkmcnt(4)
	v_mfma_f32_32x32x16_bf16 v[32:47], v[4:7], v[12:15], v[32:47]
	v_mfma_f32_32x32x16_bf16 v[16:31], v[8:11], v[12:15], v[16:31]
	v_mfma_f32_32x32x16_bf16 v[48:63], v[4:7], v[142:145], v[48:63]
	v_mfma_f32_32x32x16_bf16 v[64:79], v[8:11], v[142:145], v[64:79]
	s_waitcnt lgkmcnt(0)
	v_mfma_f32_32x32x16_bf16 v[32:47], v[146:149], v[154:157], v[32:47]
	v_mfma_f32_32x32x16_bf16 v[16:31], v[150:153], v[154:157], v[16:31]
	v_mfma_f32_32x32x16_bf16 v[48:63], v[146:149], v[158:161], v[48:63]
	v_mfma_f32_32x32x16_bf16 v[64:79], v[150:153], v[158:161], v[64:79]
	s_add_i32 s26, s26, 1
	s_cmp_eq_u32 s26, 3
	s_cselect_b32 vcc_lo, 0xfffdc000, 0
	s_cselect_b32 s26, 0, s26
	s_add_i32 vcc_lo, vcc_lo, 0xc000
	v_add_u32_e32 v166, vcc_lo, v166
	v_add_u32_e32 v170, vcc_lo, v170
	v_add_u32_e32 v167, vcc_lo, v167
	v_add_u32_e32 v171, vcc_lo, v171
	v_add_u32_e32 v168, vcc_lo, v168
	v_add_u32_e32 v172, vcc_lo, v172
	v_add_u32_e32 v169, vcc_lo, v169
	v_add_u32_e32 v173, vcc_lo, v173
	s_waitcnt vmcnt(0)
	s_barrier
	ds_read_b128 v[4:7], v166
	ds_read_b128 v[8:11], v166 offset:4096
	ds_read_b128 v[12:15], v170 offset:32768
	ds_read_b128 v[142:145], v170 offset:36864
	ds_read_b128 v[146:149], v167
	ds_read_b128 v[150:153], v167 offset:4096
	ds_read_b128 v[154:157], v171 offset:32768
	ds_read_b128 v[158:161], v171 offset:36864
	s_waitcnt lgkmcnt(4)
	v_mfma_f32_32x32x16_bf16 v[32:47], v[4:7], v[12:15], v[32:47]
	v_mfma_f32_32x32x16_bf16 v[16:31], v[8:11], v[12:15], v[16:31]
	v_mfma_f32_32x32x16_bf16 v[48:63], v[4:7], v[142:145], v[48:63]
	v_mfma_f32_32x32x16_bf16 v[64:79], v[8:11], v[142:145], v[64:79]
	ds_read_b128 v[4:7], v168
	ds_read_b128 v[8:11], v168 offset:4096
	ds_read_b128 v[12:15], v172 offset:32768
	ds_read_b128 v[142:145], v172 offset:36864
	s_waitcnt lgkmcnt(4)
	v_mfma_f32_32x32x16_bf16 v[32:47], v[146:149], v[154:157], v[32:47]
	v_mfma_f32_32x32x16_bf16 v[16:31], v[150:153], v[154:157], v[16:31]
	v_mfma_f32_32x32x16_bf16 v[48:63], v[146:149], v[158:161], v[48:63]
	v_mfma_f32_32x32x16_bf16 v[64:79], v[150:153], v[158:161], v[64:79]
	ds_read_b128 v[146:149], v169
	ds_read_b128 v[150:153], v169 offset:4096
	ds_read_b128 v[154:157], v173 offset:32768
	ds_read_b128 v[158:161], v173 offset:36864
	s_waitcnt lgkmcnt(4)
	v_mfma_f32_32x32x16_bf16 v[32:47], v[4:7], v[12:15], v[32:47]
	v_mfma_f32_32x32x16_bf16 v[16:31], v[8:11], v[12:15], v[16:31]
	v_mfma_f32_32x32x16_bf16 v[48:63], v[4:7], v[142:145], v[48:63]
	v_mfma_f32_32x32x16_bf16 v[64:79], v[8:11], v[142:145], v[64:79]
	s_waitcnt lgkmcnt(0)
	v_mfma_f32_32x32x16_bf16 v[32:47], v[146:149], v[154:157], v[32:47]
	v_mfma_f32_32x32x16_bf16 v[16:31], v[150:153], v[154:157], v[16:31]
	v_mfma_f32_32x32x16_bf16 v[48:63], v[146:149], v[158:161], v[48:63]
	v_mfma_f32_32x32x16_bf16 v[64:79], v[150:153], v[158:161], v[64:79]
	s_barrier
	v_mov_b32_e32 v0, v1
	v_readlane_b32 s4, v254, 0
	v_readlane_b32 s5, v254, 1
	v_readlane_b32 s6, v254, 2
	v_readlane_b32 s7, v254, 3
	v_readlane_b32 s8, v254, 4
	v_readlane_b32 s9, v254, 5
	v_readlane_b32 s10, v254, 6
	v_readlane_b32 s11, v254, 7
	v_readlane_b32 s12, v254, 8
	v_readlane_b32 s13, v254, 9
	v_readlane_b32 s14, v254, 10
	v_readlane_b32 s15, v254, 11
	v_readlane_b32 s16, v254, 12
	v_readlane_b32 s17, v254, 13
	v_readlane_b32 s18, v254, 14
	v_readlane_b32 s19, v254, 15
	s_nop 7
	v_add_u32_e32 v2, s20, v123
	s_movk_i32 s1, 0x1000
	v_cmp_gt_i32_e64 s[42:43], s1, v2
	v_add_u32_e32 v3, 0xfffff000, v2
	s_movk_i32 s1, 0xfff
	v_lshrrev_b32_e32 v3, 11, v3
	v_ashrrev_i32_e32 v10, 8, v2
	v_cmp_lt_i32_e64 s[44:45], s1, v2
	ds_write2_b32 v141, v32, v48 offset1:32
	ds_write2_b32 v141, v33, v49 offset0:65 offset1:97
	ds_write2_b32 v141, v34, v50 offset0:130 offset1:162
	ds_write2_b32 v141, v35, v51 offset0:195 offset1:227
	v_cndmask_b32_e64 v9, v10, v3, s[44:45]
	v_and_b32_e32 v3, 0x7c0, v2
	v_cndmask_b32_e64 v8, v127, v3, s[44:45]
	v_add_u32_e32 v3, 0x800, v141
	ds_write2_b32 v3, v36, v52 offset0:8 offset1:40
	ds_write2_b32 v3, v37, v53 offset0:73 offset1:105
	ds_write2_b32 v3, v38, v54 offset0:138 offset1:170
	ds_write2_b32 v3, v39, v55 offset0:203 offset1:235
	v_add_u32_e32 v3, 0x1000, v141
	ds_write2_b32 v3, v40, v56 offset0:16 offset1:48
	ds_write2_b32 v3, v41, v57 offset0:81 offset1:113
	ds_write2_b32 v3, v42, v58 offset0:146 offset1:178
	ds_write2_b32 v3, v43, v59 offset0:211 offset1:243
	v_add_u32_e32 v3, 0x1800, v141
	ds_write2_b32 v3, v44, v60 offset0:24 offset1:56
	ds_write2_b32 v3, v45, v61 offset0:89 offset1:121
	ds_write2_b32 v3, v46, v62 offset0:154 offset1:186
	ds_write2_b32 v3, v47, v63 offset0:219 offset1:251
	v_add_u32_e32 v3, 0x2000, v141
	ds_write2_b32 v3, v16, v64 offset0:32 offset1:64
	ds_write2_b32 v3, v17, v65 offset0:97 offset1:129
	ds_write2_b32 v3, v18, v66 offset0:162 offset1:194
	v_add_u32_e32 v3, 0x2200, v141
	ds_write2_b32 v3, v19, v67 offset0:99 offset1:131
	v_add_u32_e32 v3, 0x2800, v141
	ds_write2_b32 v3, v20, v68 offset0:40 offset1:72
	ds_write2_b32 v3, v21, v69 offset0:105 offset1:137
	ds_write2_b32 v3, v22, v70 offset0:170 offset1:202
	v_add_u32_e32 v3, 0x2a00, v141
	ds_write2_b32 v3, v23, v71 offset0:107 offset1:139
	v_add_u32_e32 v3, 0x3000, v141
	ds_write2_b32 v3, v24, v72 offset0:48 offset1:80
	ds_write2_b32 v3, v25, v73 offset0:113 offset1:145
	ds_write2_b32 v3, v26, v74 offset0:178 offset1:210
	v_add_u32_e32 v3, 0x3200, v141
	v_or_b32_e32 v0, s0, v124
	s_movk_i32 s1, 0x3ff
	ds_write2_b32 v3, v27, v75 offset0:115 offset1:147
	v_add_u32_e32 v3, 0x3800, v141
	v_cmp_lt_i32_e32 vcc, s1, v0
	ds_write2_b32 v3, v28, v76 offset0:56 offset1:88
	ds_write2_b32 v3, v29, v77 offset0:121 offset1:153
	ds_write2_b32 v3, v30, v78 offset0:186 offset1:218
	v_add_u32_e32 v3, 0x3a00, v141
	ds_write2_b32 v3, v31, v79 offset0:123 offset1:155
	s_waitcnt lgkmcnt(0)
	s_barrier
	s_and_saveexec_b64 s[20:21], vcc
	s_xor_b64 s[28:29], exec, s[20:21]
	s_cbranch_execz .LBB0_880
	s_cmpk_gt_u32 s0, 0x5ff
	s_mov_b64 s[0:1], -1
	s_cbranch_scc0 .LBB0_873
	v_readlane_b32 s4, v253, 46
	v_readlane_b32 s12, v253, 54
	v_readlane_b32 s13, v253, 55
	s_movk_i32 s0, 0x1c00
	s_mov_b32 s20, 1
	v_mov_b64_e32 v[4:5], s[12:13]
	v_mad_i64_i32 v[2:3], s[0:1], v2, s0, v[4:5]
	v_lshl_add_u64 v[2:3], v[0:1], 2, v[2:3]
	v_lshlrev_b32_e32 v4, 2, v104
	v_mov_b32_e32 v5, v1
	s_movk_i32 s0, 0xe800
	v_lshl_add_u64 v[2:3], v[2:3], 0, v[4:5]
	s_mov_b32 s1, -1
	v_lshl_add_u64 v[2:3], v[2:3], 0, s[0:1]
	s_mov_b32 s21, 0
	s_mov_b32 s22, 64
	v_readlane_b32 s5, v253, 47
	v_readlane_b32 s6, v253, 48
	v_readlane_b32 s7, v253, 49
	v_readlane_b32 s8, v253, 50
	v_readlane_b32 s9, v253, 51
	v_readlane_b32 s10, v253, 52
	v_readlane_b32 s11, v253, 53
	v_readlane_b32 s14, v253, 56
	v_readlane_b32 s15, v253, 57
	v_readlane_b32 s16, v253, 58
	v_readlane_b32 s17, v253, 59
	v_readlane_b32 s18, v253, 60
	v_readlane_b32 s19, v253, 61
